# attention loop: V fragments read early into dedicated registers (latency hidden under QK), PV MFMAs back to back
# speedup vs baseline: 1.0020x; 1.0020x over previous
; #define MFMA(a, b, c) __builtin_amdgcn_mfma_f32_32x32x16_bf16((a), (b), (c), 0, 0, 0)
; DI f32x16 zero16() { f32x16 z; _Pragma("unroll") for (int i = 0; i < 16; ++i) z[i] = 0.f; return z; }
; DI void attn_item(const Params& p, const bf16_t* Qbase  , int bh, int q0, int nkeys, int out_row0, unsigned char* smem) {
;     ...
;     for (int kt = 0; kt < nkt; ++kt) {
;         const int buf = kt & 1;
;         if (kt + 1 < nkt) gload(kt + 1);
;         __builtin_amdgcn_sched_barrier(0);
;         f32x16 s0 = zero16(), s1 = zero16();
;         const bf16_t* kb = Ks + (buf * 64 + li) * KS + 8 * lh;
; #pragma unroll
;         for (int ks = 0; ks < 6; ++ks) { s0 = MFMA(ld8(kb + 16 * ks), qf[ks], s0); s1 = MFMA(ld8(kb + 32 * KS + 16 * ks), qf[ks], s1); }
;         float mx = fmaxf(s0[0], s1[0]);
; #pragma unroll
;         for (int r = 1; r < 16; ++r) mx = fmaxf(fmaxf(mx, s0[r]), s1[r]);
;         mx = fmaxf(mx, __shfl_xor(mx, 32));
;         const float mn = fmaxf(m, mx);
;         if (__any(mn > m)) {
;             const float corr = __builtin_amdgcn_exp2f((m - mn) * scl);
;             l *= corr;
; #pragma unroll
;             for (int r = 0; r < 16; ++r) { o0[r] *= corr; o1[r] *= corr; }
;             m = mn;
;         }
;     ...
;         const bf16_t* vb = Vs + (buf * 64 + li) * VS + 4 * lh;
; #pragma unroll
;         for (int j = 0; j < 2; ++j)
; #pragma unroll
;             for (int s = 0; s < 2; ++s) {
;                 const int ko = 32 * j + 16 * s;
;                 o0 = MFMA(ld4x2(vb + ko, vb + ko + 8), pf[j][s], o0);
;                 o1 = MFMA(ld4x2(vb + 32 * VS + ko, vb + 32 * VS + ko + 8), pf[j][s], o1);
.LBB0_414:
	global_load_dwordx4 v[108:111], v122, s[26:27]
	global_load_dwordx4 v[104:107], v124, s[26:27]
	global_load_dwordx4 v[100:103], v126, s[26:27]
	global_load_dwordx4 v[96:99], v118, s[26:27]
	global_load_dwordx4 v[92:95], v120, s[26:27]
	s_and_b32 s9, s8, 64
	s_mul_i32 s12, s9, 0xd0
	s_mul_i32 s13, s9, 0x88
	v_add_u32_e32 v137, s12, v154
	v_add_u32_e32 v148, s13, v155
	v_add_u32_e32 v151, s13, v156
	ds_read_b128 v[202:205], v137
	ds_read_b128 v[206:209], v137 offset:6656
	ds_read_b128 v[210:213], v137 offset:32
	ds_read_b128 v[214:217], v137 offset:6688
	ds_read_b128 v[218:221], v137 offset:64
	s_waitcnt lgkmcnt(4)
	v_mfma_f32_32x32x16_bf16 v[36:51], v[202:205], v[88:91], 0
	ds_read_b128 v[202:205], v137 offset:6720
	s_waitcnt lgkmcnt(4)
	v_mfma_f32_32x32x16_bf16 v[52:67], v[206:209], v[88:91], 0
	ds_read_b128 v[206:209], v137 offset:96
	s_waitcnt lgkmcnt(4)
	v_mfma_f32_32x32x16_bf16 v[36:51], v[210:213], v[84:87], v[36:51]
	ds_read_b128 v[210:213], v137 offset:6752
	s_waitcnt lgkmcnt(4)
	v_mfma_f32_32x32x16_bf16 v[52:67], v[214:217], v[84:87], v[52:67]
	ds_read_b128 v[214:217], v137 offset:128
	s_waitcnt lgkmcnt(4)
	v_mfma_f32_32x32x16_bf16 v[36:51], v[218:221], v[80:83], v[36:51]
	ds_read_b128 v[218:221], v137 offset:6784
	s_waitcnt lgkmcnt(4)
	v_mfma_f32_32x32x16_bf16 v[52:67], v[202:205], v[80:83], v[52:67]
	ds_read_b128 v[202:205], v137 offset:160
	s_waitcnt lgkmcnt(4)
	v_mfma_f32_32x32x16_bf16 v[36:51], v[206:209], v[76:79], v[36:51]
	ds_read_b128 v[206:209], v137 offset:6816
	s_waitcnt lgkmcnt(4)
	v_mfma_f32_32x32x16_bf16 v[52:67], v[210:213], v[76:79], v[52:67]
	ds_read2_b64 v[164:167], v148 offset1:2
	ds_read2_b64 v[176:179], v151 offset0:32 offset1:34
	s_waitcnt lgkmcnt(5)
	v_mfma_f32_32x32x16_bf16 v[36:51], v[214:217], v[72:75], v[36:51]
	ds_read2_b64 v[192:195], v148 offset0:4 offset1:6
	ds_read2_b64 v[196:199], v151 offset0:36 offset1:38
	s_waitcnt lgkmcnt(6)
	v_mfma_f32_32x32x16_bf16 v[52:67], v[218:221], v[72:75], v[52:67]
	ds_read2_b64 v[224:227], v148 offset0:8 offset1:10
	ds_read2_b64 v[228:231], v151 offset0:40 offset1:42
	s_waitcnt lgkmcnt(7)
	v_mfma_f32_32x32x16_bf16 v[36:51], v[202:205], v[68:71], v[36:51]
	ds_read2_b64 v[244:247], v148 offset0:12 offset1:14
	ds_read2_b64 v[248:251], v151 offset0:44 offset1:46
	s_waitcnt lgkmcnt(8)
	v_mfma_f32_32x32x16_bf16 v[52:67], v[206:209], v[68:71], v[52:67]
	s_nop 11
	v_max3_f32 v137, v36, v37, v38
	v_max3_f32 v139, v52, v53, v54
	v_max3_f32 v137, v137, v39, v40
	v_max3_f32 v139, v139, v55, v56
	v_max3_f32 v137, v137, v41, v42
	v_max3_f32 v139, v139, v57, v58
	v_max3_f32 v137, v137, v43, v44
	v_max3_f32 v139, v139, v59, v60
	v_max3_f32 v137, v137, v45, v46
	v_max3_f32 v139, v139, v61, v62
	v_max3_f32 v137, v137, v47, v48
	v_max3_f32 v139, v139, v63, v64
	v_max3_f32 v137, v137, v49, v50
	v_max3_f32 v139, v139, v65, v66
	v_max3_f32 v137, v137, v51, v139
	v_max_f32_e32 v137, v137, v67
	v_mov_b32_e32 v140, v137
	v_mov_b32_e32 v141, v137
	s_nop 1
	v_permlane32_swap_b32_e32 v140, v141
	v_max3_f32 v139, v137, v140, v141
	v_max_f32_e32 v137, v136, v139
	v_cmp_gt_f32_e32 vcc, v137, v136
	s_cbranch_vccz .Lattn_keep
	v_sub_f32_e32 v136, v136, v137
	v_mul_f32_e32 v136, 0x3e16c740, v136
	v_exp_f32_e32 v136, v136
	s_nop 0
	v_pk_mul_f32 v[4:5], v[4:5], v[136:137] op_sel_hi:[1,0]
	v_pk_mul_f32 v[6:7], v[6:7], v[136:137] op_sel_hi:[1,0]
	v_pk_mul_f32 v[8:9], v[8:9], v[136:137] op_sel_hi:[1,0]
	v_pk_mul_f32 v[10:11], v[10:11], v[136:137] op_sel_hi:[1,0]
	v_pk_mul_f32 v[12:13], v[12:13], v[136:137] op_sel_hi:[1,0]
	v_pk_mul_f32 v[14:15], v[14:15], v[136:137] op_sel_hi:[1,0]
	v_pk_mul_f32 v[16:17], v[16:17], v[136:137] op_sel_hi:[1,0]
	v_pk_mul_f32 v[18:19], v[18:19], v[136:137] op_sel_hi:[1,0]
	v_pk_mul_f32 v[20:21], v[20:21], v[136:137] op_sel_hi:[1,0]
	v_pk_mul_f32 v[22:23], v[22:23], v[136:137] op_sel_hi:[1,0]
	v_pk_mul_f32 v[24:25], v[24:25], v[136:137] op_sel_hi:[1,0]
	v_pk_mul_f32 v[26:27], v[26:27], v[136:137] op_sel_hi:[1,0]
	v_pk_mul_f32 v[28:29], v[28:29], v[136:137] op_sel_hi:[1,0]
	v_pk_mul_f32 v[30:31], v[30:31], v[136:137] op_sel_hi:[1,0]
	v_pk_mul_f32 v[32:33], v[32:33], v[136:137] op_sel_hi:[1,0]
	v_pk_mul_f32 v[34:35], v[34:35], v[136:137] op_sel_hi:[1,0]
	v_mul_f32_e32 v0, v0, v136
; #define MFMA(a, b, c) __builtin_amdgcn_mfma_f32_32x32x16_bf16((a), (b), (c), 0, 0, 0)
; DI void attn_item(const Params& p, const bf16_t* Qbase  , int bh, int q0, int nkeys, int out_row0, unsigned char* smem) {
;     ...
;         const float nb = -m * scl;
;         float sum0 = 0.f, sum1 = 0.f;
; #pragma unroll
;         for (int r = 0; r < 16; ++r) { s0[r] = __builtin_amdgcn_exp2f(fmaf(s0[r], scl, nb)); s1[r] = __builtin_amdgcn_exp2f(fmaf(s1[r], scl, nb)); sum0 += s0[r]; sum1 += s1[r]; }
;         float sum = sum0 + sum1;
;         sum += __shfl_xor(sum, 32);
;         l += sum;
;         bf16x8 pf[2][2];
;         pf[0][0] = pack8(s0[0], s0[1], s0[2], s0[3], s0[4], s0[5], s0[6], s0[7]); pf[0][1] = pack8(s0[8], s0[9], s0[10], s0[11], s0[12], s0[13], s0[14], s0[15]);
;         pf[1][0] = pack8(s1[0], s1[1], s1[2], s1[3], s1[4], s1[5], s1[6], s1[7]); pf[1][1] = pack8(s1[8], s1[9], s1[10], s1[11], s1[12], s1[13], s1[14], s1[15]);
;         const bf16_t* vb = Vs + (buf * 64 + li) * VS + 4 * lh;
; #pragma unroll
;         for (int j = 0; j < 2; ++j)
; #pragma unroll
;             for (int s = 0; s < 2; ++s) {
;                 const int ko = 32 * j + 16 * s;
;                 o0 = MFMA(ld4x2(vb + ko, vb + ko + 8), pf[j][s], o0);
;                 o1 = MFMA(ld4x2(vb + 32 * VS + ko, vb + 32 * VS + ko + 8), pf[j][s], o1);
;             }
;         __builtin_amdgcn_sched_barrier(0);
;         if (kt + 1 < nkt) sstore(buf ^ 1);
;         __syncthreads();
;     }
.Lattn_keep:
	v_mul_f32_e32 v136, 0xbe16c740, v137
	v_fmamk_f32 v36, v36, 0x3e16c740, v136
	v_fmamk_f32 v37, v37, 0x3e16c740, v136
	v_exp_f32_e32 v36, v36
	v_fmamk_f32 v38, v38, 0x3e16c740, v136
	v_exp_f32_e32 v37, v37
	v_fmamk_f32 v39, v39, 0x3e16c740, v136
	v_exp_f32_e32 v38, v38
	v_fmamk_f32 v40, v40, 0x3e16c740, v136
	v_exp_f32_e32 v39, v39
	v_fmamk_f32 v41, v41, 0x3e16c740, v136
	v_exp_f32_e32 v40, v40
	v_fmamk_f32 v42, v42, 0x3e16c740, v136
	v_exp_f32_e32 v41, v41
	v_fmamk_f32 v43, v43, 0x3e16c740, v136
	v_exp_f32_e32 v42, v42
	v_fmamk_f32 v44, v44, 0x3e16c740, v136
	v_exp_f32_e32 v43, v43
	v_fmamk_f32 v45, v45, 0x3e16c740, v136
	v_exp_f32_e32 v44, v44
	v_fmamk_f32 v46, v46, 0x3e16c740, v136
	v_exp_f32_e32 v45, v45
	v_fmamk_f32 v47, v47, 0x3e16c740, v136
	v_exp_f32_e32 v46, v46
	v_fmamk_f32 v48, v48, 0x3e16c740, v136
	v_exp_f32_e32 v47, v47
	v_fmamk_f32 v49, v49, 0x3e16c740, v136
	v_exp_f32_e32 v48, v48
	v_fmamk_f32 v50, v50, 0x3e16c740, v136
	v_exp_f32_e32 v49, v49
	v_fmamk_f32 v51, v51, 0x3e16c740, v136
	v_exp_f32_e32 v50, v50
	v_fmamk_f32 v52, v52, 0x3e16c740, v136
	v_exp_f32_e32 v51, v51
	v_fmamk_f32 v53, v53, 0x3e16c740, v136
	v_exp_f32_e32 v52, v52
	v_fmamk_f32 v54, v54, 0x3e16c740, v136
	v_exp_f32_e32 v53, v53
	v_fmamk_f32 v55, v55, 0x3e16c740, v136
	v_exp_f32_e32 v54, v54
	v_fmamk_f32 v56, v56, 0x3e16c740, v136
	v_exp_f32_e32 v55, v55
	v_fmamk_f32 v57, v57, 0x3e16c740, v136
	v_exp_f32_e32 v56, v56
	v_fmamk_f32 v58, v58, 0x3e16c740, v136
	v_exp_f32_e32 v57, v57
	v_fmamk_f32 v59, v59, 0x3e16c740, v136
	v_exp_f32_e32 v58, v58
	v_fmamk_f32 v60, v60, 0x3e16c740, v136
	v_exp_f32_e32 v59, v59
	v_fmamk_f32 v61, v61, 0x3e16c740, v136
	v_exp_f32_e32 v60, v60
	v_fmamk_f32 v62, v62, 0x3e16c740, v136
	v_exp_f32_e32 v61, v61
	v_fmamk_f32 v63, v63, 0x3e16c740, v136
	v_exp_f32_e32 v62, v62
	v_fmamk_f32 v64, v64, 0x3e16c740, v136
	v_exp_f32_e32 v63, v63
	v_fmamk_f32 v65, v65, 0x3e16c740, v136
	v_exp_f32_e32 v64, v64
	v_fmamk_f32 v66, v66, 0x3e16c740, v136
	v_exp_f32_e32 v65, v65
	v_fmamk_f32 v67, v67, 0x3e16c740, v136
	v_exp_f32_e32 v66, v66
	v_exp_f32_e32 v67, v67
	v_add_f32_e32 v138, v36, v37
	v_add_f32_e32 v139, v44, v45
	v_add_f32_e32 v152, v52, v53
	v_add_f32_e32 v153, v60, v61
	v_add_f32_e32 v138, v138, v38
	v_add_f32_e32 v139, v139, v46
	v_add_f32_e32 v152, v152, v54
	v_add_f32_e32 v153, v153, v62
	v_add_f32_e32 v138, v138, v39
	v_add_f32_e32 v139, v139, v47
	v_add_f32_e32 v152, v152, v55
	v_add_f32_e32 v153, v153, v63
	v_add_f32_e32 v138, v138, v40
	v_add_f32_e32 v139, v139, v48
	v_add_f32_e32 v152, v152, v56
	v_add_f32_e32 v153, v153, v64
	v_add_f32_e32 v138, v138, v41
	v_add_f32_e32 v139, v139, v49
	v_add_f32_e32 v152, v152, v57
	v_add_f32_e32 v153, v153, v65
	v_add_f32_e32 v138, v138, v42
	v_add_f32_e32 v139, v139, v50
	v_add_f32_e32 v152, v152, v58
	v_add_f32_e32 v153, v153, v66
	v_add_f32_e32 v138, v138, v43
	v_add_f32_e32 v139, v139, v51
	v_add_f32_e32 v152, v152, v59
	v_add_f32_e32 v153, v153, v67
	v_cvt_pk_bf16_f32 v140, v52, v53
	v_cvt_pk_bf16_f32 v141, v54, v55
	v_cvt_pk_bf16_f32 v142, v56, v57
	v_cvt_pk_bf16_f32 v143, v58, v59
	v_cvt_pk_bf16_f32 v144, v60, v61
	v_cvt_pk_bf16_f32 v145, v62, v63
	v_cvt_pk_bf16_f32 v146, v64, v65
	v_cvt_pk_bf16_f32 v147, v66, v67
	v_cvt_pk_bf16_f32 v36, v36, v37
	v_cvt_pk_bf16_f32 v37, v38, v39
	v_cvt_pk_bf16_f32 v38, v40, v41
	v_cvt_pk_bf16_f32 v39, v42, v43
	v_cvt_pk_bf16_f32 v40, v44, v45
	v_cvt_pk_bf16_f32 v41, v46, v47
	v_cvt_pk_bf16_f32 v42, v48, v49
	v_cvt_pk_bf16_f32 v43, v50, v51
	v_add_f32_e32 v138, v138, v139
	v_add_f32_e32 v152, v152, v153
	v_add_f32_e32 v138, v138, v152
	v_add_f32_e32 v0, v0, v138
	s_waitcnt lgkmcnt(0)
	v_mfma_f32_32x32x16_bf16 v[4:19], v[164:167], v[36:39], v[4:19]
	v_mfma_f32_32x32x16_bf16 v[20:35], v[176:179], v[36:39], v[20:35]
	v_mfma_f32_32x32x16_bf16 v[4:19], v[192:195], v[40:43], v[4:19]
	v_mfma_f32_32x32x16_bf16 v[20:35], v[196:199], v[40:43], v[20:35]
	v_mfma_f32_32x32x16_bf16 v[4:19], v[224:227], v[140:143], v[4:19]
	v_mfma_f32_32x32x16_bf16 v[20:35], v[228:231], v[140:143], v[20:35]
	v_mfma_f32_32x32x16_bf16 v[4:19], v[244:247], v[144:147], v[4:19]
	v_mfma_f32_32x32x16_bf16 v[20:35], v[248:251], v[144:147], v[20:35]
	s_xor_b32 s9, s9, 64
	s_mul_i32 s12, s9, 0xd0
	s_mul_i32 s13, s9, 0x88
	v_add_u32_e32 v36, s12, v157
	s_waitcnt vmcnt(4)
	ds_write_b128 v36, v[108:111]
	v_add_u32_e32 v36, s12, v158
	s_waitcnt vmcnt(3)
	ds_write_b128 v36, v[104:107]
	v_add_u32_e32 v36, s12, v159
	s_waitcnt vmcnt(2)
	ds_write_b128 v36, v[100:103]
	v_add_u32_e32 v36, s13, v160
	s_waitcnt vmcnt(1)
	ds_write2_b64 v36, v[96:97], v[98:99] offset1:1
	v_add_u32_e32 v36, s13, v161
	s_add_i32 s8, s8, 64
	v_add_u32_e32 v122, 0x3000, v122
	v_add_u32_e32 v124, 0x3000, v124
	v_add_u32_e32 v126, 0x3000, v126
	v_add_u32_e32 v118, 0x80, v118
	v_add_u32_e32 v120, 0x80, v120
	s_mov_b64 s[10:11], 0x3000
	s_movk_i32 s12, 0x88
	s_movk_i32 s13, 0xd0
	s_movk_i32 s37, 0xd0
	s_movk_i32 s71, 0x88
	s_mov_b64 s[68:69], 0x3000
	s_waitcnt vmcnt(0)
	ds_write2_b64 v36, v[92:93], v[94:95] offset1:1
	s_waitcnt lgkmcnt(0)
	s_barrier
	s_cmpk_eq_i32 s8, 0x10c0
	s_cbranch_scc1 .Lattn_exit
	v_mov_b32_e32 v136, v137
	s_branch .LBB0_414
